# P6 residual epilogue: f32 x values fetched three groups ahead as global loads through a 4-slot register ring, counted waits (was 16 serial flat-load round trips per tile) (on v65)
# speedup vs baseline: 1.0212x; 1.0034x over previous
; __device__ __forceinline__ unsigned pk2(float lo, float hi) { f32x2 v = {lo, hi}; bf16x2_t b = __builtin_convertvector(v, bf16x2_t); return __builtin_bit_cast(unsigned, b); }
;     __device__ __forceinline__ void operator()(const f32x4 (&acc)[2][2][4][2], const Unit& u, int wr, int wc, int fr, int fq) const {
;         const int row0 = u.pm * BM + wr * 64 + fr; const int b = (u.pm * BM) / S;
;         f32x4 gv[2][2];
; #pragma unroll
;         for (int bj = 0; bj < 2; ++bj)
; #pragma unroll
;             for (int n = 0; n < 2; ++n) gv[bj][n] = *(const f32x4*)(gate + (size_t)b * 6144 + u.pn * BM + bj * HALF + wc * 32 + 8 * fq + 4 * n);
; #pragma unroll
;         for (int ai = 0; ai < 2; ++ai)
; #pragma unroll
;             for (int m = 0; m < 4; ++m) { const size_t off = (size_t)(row0 + ai * HALF + m * 16) * D + u.pn * BM + wc * 32 + 8 * fq;
; #pragma unroll
;                 for (int bj = 0; bj < 2; ++bj) { const size_t o = off + bj * HALF; f32x4 b0, b1;
;                     if (BASE_BF16) { const u32x4 r = *(const u32x4*)((const bf16_t*)base + o);
;                         b0 = (f32x4){__uint_as_float(r.x << 16), __uint_as_float(r.x & 0xffff0000u), __uint_as_float(r.y << 16), __uint_as_float(r.y & 0xffff0000u)};
;                         b1 = (f32x4){__uint_as_float(r.z << 16), __uint_as_float(r.z & 0xffff0000u), __uint_as_float(r.w << 16), __uint_as_float(r.w & 0xffff0000u)}; }
;                     else { b0 = *(const f32x4*)((const float*)base + o); b1 = *(const f32x4*)((const float*)base + o + 4); }
;                     const f32x4 v0 = b0 + gv[bj][0] * acc[ai][bj][m][0], v1 = b1 + gv[bj][1] * acc[ai][bj][m][1];
;                     u32x4 w; w.x = pk2(v0[0], v0[1]); w.y = pk2(v0[2], v0[3]); w.z = pk2(v1[0], v1[1]); w.w = pk2(v1[2], v1[3]);
;                     *(u32x4*)(out + o) = w; } }
.LBB0_920:
	s_ashr_i32 s27, s34, 31
	s_lshr_b32 s27, s27, 29
	s_add_i32 s27, s34, s27
	s_lshl_b32 s25, s34, 8
	s_ashr_i32 s27, s27, 3
	s_add_i32 s25, s25, s54
	s_mul_hi_i32 s34, s27, 0x6000
	s_mulk_i32 s27, 0x6000
	s_add_u32 s27, s49, s27
	s_addc_u32 s34, s51, s34
	s_lshl_b32 s36, s62, 8
	s_ashr_i32 s37, s36, 31
	s_lshl_b64 s[38:39], s[36:37], 2
	s_add_u32 s27, s27, s38
	v_mbcnt_lo_u32_b32 v130, -1, 0
	v_mbcnt_hi_u32_b32 v130, -1, v130
	s_addc_u32 s34, s34, s39
	v_ashrrev_i32_e32 v128, 1, v130
	s_add_u32 s38, s27, s60
	v_and_b32_e32 v128, -8, v128
	v_and_or_b32 v174, v130, 15, s25
	s_addc_u32 s39, s34, 0
	v_ashrrev_i32_e32 v129, 31, v128
	s_or_b64 s[36:37], s[36:37], s[8:9]
	v_ashrrev_i32_e32 v175, 31, v174
	v_lshl_add_u64 v[132:133], v[128:129], 2, s[38:39]
	v_lshl_add_u64 v[176:177], s[36:37], 0, v[128:129]
	v_lshlrev_b64 v[128:129], 10, v[174:175]
	v_lshl_add_u64 v[160:161], v[176:177], 0, v[128:129]
	v_lshl_add_u64 v[178:179], v[160:161], 2, s[6:7]
	global_load_dwordx4 v[140:143], v[132:133], off
	global_load_dwordx4 v[136:139], v[132:133], off offset:16
	global_load_dwordx4 v[128:131], v[132:133], off offset:528
	s_nop 0
	global_load_dwordx4 v[132:135], v[132:133], off offset:512
	v_lshl_add_u64 v[180:181], v[160:161], 1, s[44:45]
	s_andn2_b64 vcc, exec, s[4:5]
	s_mov_b64 s[4:5], -1
	global_load_dwordx4 v[214:217], v[178:179], off
	global_load_dwordx4 v[218:221], v[178:179], off offset:16
	global_load_dwordx4 v[222:225], v[178:179], off offset:512
	global_load_dwordx4 v[226:229], v[178:179], off offset:528
	s_mov_b64 s[98:99], 0x10000
	v_lshl_add_u64 v[246:247], v[178:179], 0, s[98:99]
	global_load_dwordx4 v[230:233], v[246:247], off
	global_load_dwordx4 v[234:237], v[246:247], off offset:16
	s_waitcnt vmcnt(4) lgkmcnt(0)
	v_pk_fma_f32 v[126:127], v[126:127], v[142:143], v[216:217]
	v_pk_fma_f32 v[124:125], v[124:125], v[140:141], v[214:215]
	v_pk_fma_f32 v[166:167], v[122:123], v[138:139], v[220:221]
	v_pk_fma_f32 v[122:123], v[120:121], v[136:137], v[218:219]
	v_cvt_pk_bf16_f32 v120, v124, v125
	v_cvt_pk_bf16_f32 v121, v126, v127
	v_cvt_pk_bf16_f32 v122, v122, v123
	v_cvt_pk_bf16_f32 v123, v166, v167
	global_store_dwordx4 v[180:181], v[120:123], off
	s_mov_b64 s[98:99], 0x10000
	v_lshl_add_u64 v[246:247], v[178:179], 0, s[98:99]
	global_load_dwordx4 v[238:241], v[246:247], off offset:512
	global_load_dwordx4 v[242:245], v[246:247], off offset:528
	s_nop 0
	v_or_b32_e32 v166, 16, v174
	v_ashrrev_i32_e32 v167, 31, v166
	v_lshlrev_b64 v[166:167], 10, v[166:167]
	v_lshl_add_u64 v[166:167], v[166:167], 0, v[176:177]
	v_lshl_add_u64 v[168:169], v[166:167], 2, s[6:7]
	s_waitcnt vmcnt(5)
	v_pk_fma_f32 v[118:119], v[118:119], v[134:135], v[224:225]
	v_pk_fma_f32 v[116:117], v[116:117], v[132:133], v[222:223]
	v_pk_fma_f32 v[120:121], v[114:115], v[130:131], v[228:229]
	v_pk_fma_f32 v[114:115], v[112:113], v[128:129], v[226:227]
	v_cvt_pk_bf16_f32 v112, v116, v117
	v_cvt_pk_bf16_f32 v113, v118, v119
	v_cvt_pk_bf16_f32 v114, v114, v115
	v_cvt_pk_bf16_f32 v115, v120, v121
	global_store_dwordx4 v[180:181], v[112:115], off offset:256
	s_mov_b64 s[98:99], 0x20000
	v_lshl_add_u64 v[246:247], v[178:179], 0, s[98:99]
	global_load_dwordx4 v[214:217], v[246:247], off
	global_load_dwordx4 v[218:221], v[246:247], off offset:16
	s_nop 0
	v_lshl_add_u64 v[120:121], v[166:167], 1, s[44:45]
	s_waitcnt vmcnt(6)
	v_pk_fma_f32 v[110:111], v[110:111], v[142:143], v[232:233]
	v_pk_fma_f32 v[108:109], v[108:109], v[140:141], v[230:231]
	v_pk_fma_f32 v[112:113], v[106:107], v[138:139], v[236:237]
	v_pk_fma_f32 v[106:107], v[104:105], v[136:137], v[234:235]
	v_cvt_pk_bf16_f32 v104, v108, v109
	v_cvt_pk_bf16_f32 v105, v110, v111
	v_cvt_pk_bf16_f32 v106, v106, v107
	v_cvt_pk_bf16_f32 v107, v112, v113
	global_store_dwordx4 v[120:121], v[104:107], off
	s_mov_b64 s[98:99], 0x20000
	v_lshl_add_u64 v[246:247], v[178:179], 0, s[98:99]
	global_load_dwordx4 v[222:225], v[246:247], off offset:512
	global_load_dwordx4 v[226:229], v[246:247], off offset:528
	s_nop 0
	v_or_b32_e32 v112, 32, v174
	v_ashrrev_i32_e32 v113, 31, v112
	v_lshlrev_b64 v[112:113], 10, v[112:113]
	v_lshl_add_u64 v[112:113], v[112:113], 0, v[176:177]
	v_lshl_add_u64 v[114:115], v[112:113], 2, s[6:7]
	s_waitcnt vmcnt(6)
	v_pk_fma_f32 v[102:103], v[102:103], v[134:135], v[240:241]
	v_pk_fma_f32 v[100:101], v[100:101], v[132:133], v[238:239]
	v_pk_fma_f32 v[104:105], v[98:99], v[130:131], v[244:245]
	v_pk_fma_f32 v[98:99], v[96:97], v[128:129], v[242:243]
	v_cvt_pk_bf16_f32 v96, v100, v101
	v_cvt_pk_bf16_f32 v97, v102, v103
	v_cvt_pk_bf16_f32 v98, v98, v99
	v_cvt_pk_bf16_f32 v99, v104, v105
	global_store_dwordx4 v[120:121], v[96:99], off offset:256
	s_mov_b64 s[98:99], 0x30000
	v_lshl_add_u64 v[246:247], v[178:179], 0, s[98:99]
	global_load_dwordx4 v[230:233], v[246:247], off
	global_load_dwordx4 v[234:237], v[246:247], off offset:16
	s_nop 0
	v_lshl_add_u64 v[104:105], v[112:113], 1, s[44:45]
	s_waitcnt vmcnt(6)
	v_pk_fma_f32 v[94:95], v[94:95], v[142:143], v[216:217]
	v_pk_fma_f32 v[92:93], v[92:93], v[140:141], v[214:215]
	v_pk_fma_f32 v[96:97], v[90:91], v[138:139], v[220:221]
	v_pk_fma_f32 v[90:91], v[88:89], v[136:137], v[218:219]
	v_cvt_pk_bf16_f32 v88, v92, v93
	v_cvt_pk_bf16_f32 v89, v94, v95
	v_cvt_pk_bf16_f32 v90, v90, v91
	v_cvt_pk_bf16_f32 v91, v96, v97
	global_store_dwordx4 v[104:105], v[88:91], off
	s_mov_b64 s[98:99], 0x30000
	v_lshl_add_u64 v[246:247], v[178:179], 0, s[98:99]
	global_load_dwordx4 v[238:241], v[246:247], off offset:512
	global_load_dwordx4 v[242:245], v[246:247], off offset:528
	s_nop 0
	v_or_b32_e32 v96, 48, v174
	v_ashrrev_i32_e32 v97, 31, v96
	v_lshlrev_b64 v[96:97], 10, v[96:97]
	v_lshl_add_u64 v[96:97], v[96:97], 0, v[176:177]
	v_lshl_add_u64 v[98:99], v[96:97], 2, s[6:7]
	s_waitcnt vmcnt(6)
; __device__ __forceinline__ unsigned pk2(float lo, float hi) { f32x2 v = {lo, hi}; bf16x2_t b = __builtin_convertvector(v, bf16x2_t); return __builtin_bit_cast(unsigned, b); }
;     __device__ __forceinline__ void operator()(const f32x4 (&acc)[2][2][4][2], const Unit& u, int wr, int wc, int fr, int fq) const {
;     ...
;         for (int ai = 0; ai < 2; ++ai)
; #pragma unroll
;             for (int m = 0; m < 4; ++m) { const size_t off = (size_t)(row0 + ai * HALF + m * 16) * D + u.pn * BM + wc * 32 + 8 * fq;
; #pragma unroll
;                 for (int bj = 0; bj < 2; ++bj) { const size_t o = off + bj * HALF; f32x4 b0, b1;
;                     if (BASE_BF16) { const u32x4 r = *(const u32x4*)((const bf16_t*)base + o);
;                         b0 = (f32x4){__uint_as_float(r.x << 16), __uint_as_float(r.x & 0xffff0000u), __uint_as_float(r.y << 16), __uint_as_float(r.y & 0xffff0000u)};
;                         b1 = (f32x4){__uint_as_float(r.z << 16), __uint_as_float(r.z & 0xffff0000u), __uint_as_float(r.w << 16), __uint_as_float(r.w & 0xffff0000u)}; }
;                     else { b0 = *(const f32x4*)((const float*)base + o); b1 = *(const f32x4*)((const float*)base + o + 4); }
;                     const f32x4 v0 = b0 + gv[bj][0] * acc[ai][bj][m][0], v1 = b1 + gv[bj][1] * acc[ai][bj][m][1];
;                     u32x4 w; w.x = pk2(v0[0], v0[1]); w.y = pk2(v0[2], v0[3]); w.z = pk2(v1[0], v1[1]); w.w = pk2(v1[2], v1[3]);
;                     *(u32x4*)(out + o) = w; } }
	v_pk_fma_f32 v[86:87], v[86:87], v[134:135], v[224:225]
	v_pk_fma_f32 v[84:85], v[84:85], v[132:133], v[222:223]
	v_pk_fma_f32 v[88:89], v[82:83], v[130:131], v[228:229]
	v_pk_fma_f32 v[82:83], v[80:81], v[128:129], v[226:227]
	v_cvt_pk_bf16_f32 v80, v84, v85
	v_cvt_pk_bf16_f32 v81, v86, v87
	v_cvt_pk_bf16_f32 v82, v82, v83
	v_cvt_pk_bf16_f32 v83, v88, v89
	global_store_dwordx4 v[104:105], v[80:83], off offset:256
	s_lshl_b64 s[98:99], s[16:17], 2
	v_lshl_add_u64 v[246:247], v[178:179], 0, s[98:99]
	global_load_dwordx4 v[214:217], v[246:247], off
	global_load_dwordx4 v[218:221], v[246:247], off offset:16
	s_nop 0
	v_lshl_add_u64 v[88:89], v[96:97], 1, s[44:45]
	s_waitcnt vmcnt(6)
	v_pk_fma_f32 v[78:79], v[78:79], v[142:143], v[232:233]
	v_pk_fma_f32 v[76:77], v[76:77], v[140:141], v[230:231]
	v_pk_fma_f32 v[80:81], v[74:75], v[138:139], v[236:237]
	v_pk_fma_f32 v[74:75], v[72:73], v[136:137], v[234:235]
	v_cvt_pk_bf16_f32 v72, v76, v77
	v_cvt_pk_bf16_f32 v73, v78, v79
	v_cvt_pk_bf16_f32 v74, v74, v75
	v_cvt_pk_bf16_f32 v75, v80, v81
	global_store_dwordx4 v[88:89], v[72:75], off
	s_lshl_b64 s[98:99], s[16:17], 2
	v_lshl_add_u64 v[246:247], v[178:179], 0, s[98:99]
	global_load_dwordx4 v[222:225], v[246:247], off offset:512
	global_load_dwordx4 v[226:229], v[246:247], off offset:528
	s_nop 0
	v_lshl_add_u64 v[80:81], v[160:161], 0, s[16:17]
	v_lshl_add_u64 v[82:83], v[80:81], 2, s[6:7]
	s_waitcnt vmcnt(6)
	v_pk_fma_f32 v[70:71], v[70:71], v[134:135], v[240:241]
	v_pk_fma_f32 v[68:69], v[68:69], v[132:133], v[238:239]
	v_pk_fma_f32 v[72:73], v[66:67], v[130:131], v[244:245]
	v_pk_fma_f32 v[66:67], v[64:65], v[128:129], v[242:243]
	v_cvt_pk_bf16_f32 v64, v68, v69
	v_cvt_pk_bf16_f32 v65, v70, v71
	v_cvt_pk_bf16_f32 v66, v66, v67
	v_cvt_pk_bf16_f32 v67, v72, v73
	global_store_dwordx4 v[88:89], v[64:67], off offset:256
	s_lshl_b64 s[98:99], s[18:19], 2
	v_lshl_add_u64 v[246:247], v[178:179], 0, s[98:99]
	global_load_dwordx4 v[230:233], v[246:247], off
	global_load_dwordx4 v[234:237], v[246:247], off offset:16
	s_nop 0
	v_lshl_add_u64 v[72:73], v[80:81], 1, s[44:45]
	s_waitcnt vmcnt(6)
	v_pk_fma_f32 v[62:63], v[62:63], v[142:143], v[216:217]
	v_pk_fma_f32 v[60:61], v[60:61], v[140:141], v[214:215]
	v_pk_fma_f32 v[64:65], v[58:59], v[138:139], v[220:221]
	v_pk_fma_f32 v[58:59], v[56:57], v[136:137], v[218:219]
	v_cvt_pk_bf16_f32 v56, v60, v61
	v_cvt_pk_bf16_f32 v57, v62, v63
	v_cvt_pk_bf16_f32 v58, v58, v59
	v_cvt_pk_bf16_f32 v59, v64, v65
	global_store_dwordx4 v[72:73], v[56:59], off
	s_lshl_b64 s[98:99], s[18:19], 2
	v_lshl_add_u64 v[246:247], v[178:179], 0, s[98:99]
	global_load_dwordx4 v[238:241], v[246:247], off offset:512
	global_load_dwordx4 v[242:245], v[246:247], off offset:528
	s_nop 0
	v_lshl_add_u64 v[64:65], v[160:161], 0, s[18:19]
	v_lshl_add_u64 v[66:67], v[64:65], 2, s[6:7]
	s_waitcnt vmcnt(6)
	v_pk_fma_f32 v[54:55], v[54:55], v[134:135], v[224:225]
	v_pk_fma_f32 v[52:53], v[52:53], v[132:133], v[222:223]
	v_pk_fma_f32 v[56:57], v[50:51], v[130:131], v[228:229]
	v_pk_fma_f32 v[50:51], v[48:49], v[128:129], v[226:227]
	v_cvt_pk_bf16_f32 v48, v52, v53
	v_cvt_pk_bf16_f32 v49, v54, v55
	v_cvt_pk_bf16_f32 v50, v50, v51
	v_cvt_pk_bf16_f32 v51, v56, v57
	global_store_dwordx4 v[72:73], v[48:51], off offset:256
	s_lshl_b64 s[98:99], s[20:21], 2
	v_lshl_add_u64 v[246:247], v[178:179], 0, s[98:99]
	global_load_dwordx4 v[214:217], v[246:247], off
	global_load_dwordx4 v[218:221], v[246:247], off offset:16
	s_nop 0
	v_lshl_add_u64 v[56:57], v[64:65], 1, s[44:45]
	s_waitcnt vmcnt(6)
	v_pk_fma_f32 v[46:47], v[46:47], v[142:143], v[232:233]
	v_pk_fma_f32 v[44:45], v[44:45], v[140:141], v[230:231]
	v_pk_fma_f32 v[48:49], v[42:43], v[138:139], v[236:237]
	v_pk_fma_f32 v[42:43], v[40:41], v[136:137], v[234:235]
	v_cvt_pk_bf16_f32 v40, v44, v45
	v_cvt_pk_bf16_f32 v41, v46, v47
	v_cvt_pk_bf16_f32 v42, v42, v43
	v_cvt_pk_bf16_f32 v43, v48, v49
	global_store_dwordx4 v[56:57], v[40:43], off
	s_lshl_b64 s[98:99], s[20:21], 2
	v_lshl_add_u64 v[246:247], v[178:179], 0, s[98:99]
	global_load_dwordx4 v[222:225], v[246:247], off offset:512
	global_load_dwordx4 v[226:229], v[246:247], off offset:528
	s_nop 0
	v_lshl_add_u64 v[48:49], v[160:161], 0, s[20:21]
	v_lshl_add_u64 v[50:51], v[48:49], 2, s[6:7]
	s_waitcnt vmcnt(6)
	v_pk_fma_f32 v[38:39], v[38:39], v[134:135], v[240:241]
	v_pk_fma_f32 v[36:37], v[36:37], v[132:133], v[238:239]
	v_pk_fma_f32 v[40:41], v[34:35], v[130:131], v[244:245]
	v_pk_fma_f32 v[34:35], v[32:33], v[128:129], v[242:243]
	v_cvt_pk_bf16_f32 v32, v36, v37
	v_cvt_pk_bf16_f32 v33, v38, v39
	v_cvt_pk_bf16_f32 v34, v34, v35
	v_cvt_pk_bf16_f32 v35, v40, v41
	global_store_dwordx4 v[56:57], v[32:35], off offset:256
	s_lshl_b64 s[98:99], s[22:23], 2
	v_lshl_add_u64 v[246:247], v[178:179], 0, s[98:99]
	global_load_dwordx4 v[230:233], v[246:247], off
	global_load_dwordx4 v[234:237], v[246:247], off offset:16
	s_nop 0
	v_lshl_add_u64 v[40:41], v[48:49], 1, s[44:45]
	s_waitcnt vmcnt(6)
	v_pk_fma_f32 v[30:31], v[30:31], v[142:143], v[216:217]
	v_pk_fma_f32 v[28:29], v[28:29], v[140:141], v[214:215]
	v_pk_fma_f32 v[32:33], v[26:27], v[138:139], v[220:221]
	v_pk_fma_f32 v[26:27], v[24:25], v[136:137], v[218:219]
	v_cvt_pk_bf16_f32 v24, v28, v29
	v_cvt_pk_bf16_f32 v25, v30, v31
	v_cvt_pk_bf16_f32 v26, v26, v27
	v_cvt_pk_bf16_f32 v27, v32, v33
	global_store_dwordx4 v[40:41], v[24:27], off
	s_lshl_b64 s[98:99], s[22:23], 2
	v_lshl_add_u64 v[246:247], v[178:179], 0, s[98:99]
	global_load_dwordx4 v[238:241], v[246:247], off offset:512
	global_load_dwordx4 v[242:245], v[246:247], off offset:528
	s_nop 0
	v_lshl_add_u64 v[32:33], v[160:161], 0, s[22:23]
	v_lshl_add_u64 v[34:35], v[32:33], 2, s[6:7]
	s_waitcnt vmcnt(6)
	v_pk_fma_f32 v[22:23], v[22:23], v[134:135], v[224:225]
	v_pk_fma_f32 v[20:21], v[20:21], v[132:133], v[222:223]
	v_pk_fma_f32 v[24:25], v[18:19], v[130:131], v[228:229]
	v_pk_fma_f32 v[18:19], v[16:17], v[128:129], v[226:227]
	v_cvt_pk_bf16_f32 v16, v20, v21
	v_cvt_pk_bf16_f32 v17, v22, v23
	v_cvt_pk_bf16_f32 v18, v18, v19
	v_cvt_pk_bf16_f32 v19, v24, v25
	global_store_dwordx4 v[40:41], v[16:19], off offset:256
	s_nop 0
	v_lshl_add_u64 v[24:25], v[32:33], 1, s[44:45]
	s_waitcnt vmcnt(4)
	v_pk_fma_f32 v[14:15], v[14:15], v[142:143], v[232:233]
	v_pk_fma_f32 v[12:13], v[12:13], v[140:141], v[230:231]
	v_pk_fma_f32 v[16:17], v[10:11], v[138:139], v[236:237]
	v_pk_fma_f32 v[10:11], v[8:9], v[136:137], v[234:235]
	v_cvt_pk_bf16_f32 v8, v12, v13
	v_cvt_pk_bf16_f32 v9, v14, v15
	v_cvt_pk_bf16_f32 v10, v10, v11
	v_cvt_pk_bf16_f32 v11, v16, v17
	global_store_dwordx4 v[24:25], v[8:11], off
	s_nop 0
	s_waitcnt vmcnt(2)
	v_pk_fma_f32 v[6:7], v[6:7], v[134:135], v[240:241]
	v_pk_fma_f32 v[4:5], v[4:5], v[132:133], v[238:239]
	v_pk_fma_f32 v[8:9], v[2:3], v[130:131], v[244:245]
	v_pk_fma_f32 v[2:3], v[0:1], v[128:129], v[242:243]
	v_cvt_pk_bf16_f32 v0, v4, v5
	v_cvt_pk_bf16_f32 v1, v6, v7
	v_cvt_pk_bf16_f32 v2, v2, v3
	v_cvt_pk_bf16_f32 v3, v8, v9
	global_store_dwordx4 v[24:25], v[0:3], off offset:256
	s_cbranch_vccnz .LBB0_909
; #define PG8_BAR __builtin_amdgcn_s_barrier()
; template <class Epi, bool ALIGN_EPI, int K, int LDA, int LDB>
; __device__ __forceinline__ void gemm_phase(LAS unsigned char* lds, const int wid, const Gemm g, const StaticOrder& S, const Epi& E) {
;     ...
;         if (!has_next) break;
; #pragma unroll
;         for (int a = 0; a < 2; ++a)
; #pragma unroll
;             for (int b = 0; b < 2; ++b)
; #pragma unroll
;                 for (int m = 0; m < 4; ++m)
; #pragma unroll
;                     for (int n = 0; n < 2; ++n) acc[a][b][m][n] = (f32x4){0.f, 0.f, 0.f, 0.f};
;         cur = nxt; cA = nA; cB = nB; ++ui;
;         if constexpr (ALIGN_EPI) { if (wr == 1) PG8_BAR; }
	s_andn2_b64 vcc, exec, s[10:11]
	s_cbranch_vccnz .LBB0_908
	s_barrier
	s_branch .LBB0_908
